# gemm_in vs/vw tiles: transposed-store image reads two rows (16 reads) in flight
# speedup vs baseline: 1.0170x; 1.0005x over previous
.LBB0_451:
	v_readlane_b32 s20, v237, 49
	v_lshlrev_b32_e32 v0, 6, v4
	v_readlane_b32 s23, v237, 52
	v_readlane_b32 s25, v237, 54
	v_cmp_eq_u32_e64 s[4:5], 23, v135
	v_and_b32_e32 v5, 64, v0
	v_readlane_b32 s22, v237, 51
	v_readlane_b32 s24, v237, 53
	v_mov_b32_e32 v0, s25
	v_mov_b32_e32 v3, s23
	v_cndmask_b32_e64 v7, v0, v3, s[4:5]
	v_mov_b32_e32 v0, s24
	v_mov_b32_e32 v3, s22
	v_cndmask_b32_e64 v6, v0, v3, s[4:5]
	v_lshrrev_b32_e32 v0, 4, v136
	v_ashrrev_i32_e32 v2, 1, v4
	v_and_b32_e32 v0, 0xffffffe, v0
	v_lshlrev_b64 v[8:9], 6, v[0:1]
	v_ashrrev_i32_e32 v3, 31, v2
	v_lshl_add_u64 v[2:3], v[8:9], 0, v[2:3]
	s_movk_i32 s18, 0x2080
	v_mad_u64_u32 v[6:7], s[4:5], v2, s18, v[6:7]
	s_movk_i32 s4, 0xf80
	s_nop 0
	v_and_or_b32 v0, v34, s4, v5
	v_mad_i32_i24 v7, v3, s18, v7
	v_lshlrev_b32_e32 v0, 1, v0
	v_lshl_add_u64 v[2:3], v[6:7], 0, v[0:1]
	v_and_b32_e32 v0, -2, v4
	s_movk_i32 s4, 0x110
	v_mad_u32_u24 v0, v5, s4, v0
	v_readlane_b32 s21, v237, 50
	v_readlane_b32 s26, v237, 55
	v_readlane_b32 s27, v237, 56
	s_movk_i32 s94, 0x2080
	s_andn2_b64 s[14:15], s[14:15], exec
	s_andn2_b64 s[12:13], s[12:13], exec
	ds_read_u16 v64, v0
	ds_read_u16 v65, v0 offset:272
	ds_read_u16 v66, v0 offset:544
	ds_read_u16 v67, v0 offset:816
	ds_read_u16 v68, v0 offset:1088
	ds_read_u16 v69, v0 offset:1360
	ds_read_u16 v70, v0 offset:1632
	ds_read_u16 v71, v0 offset:1904
	ds_read_u16 v72, v0 offset:2176
	ds_read_u16 v73, v0 offset:2448
	ds_read_u16 v74, v0 offset:2720
	ds_read_u16 v75, v0 offset:2992
	ds_read_u16 v76, v0 offset:3264
	ds_read_u16 v77, v0 offset:3536
	ds_read_u16 v78, v0 offset:3808
	ds_read_u16 v79, v0 offset:4080
	s_waitcnt lgkmcnt(8)
	v_lshl_or_b32 v128, v65, 16, v64
	v_lshl_or_b32 v129, v67, 16, v66
	v_lshl_or_b32 v130, v69, 16, v68
	v_lshl_or_b32 v131, v71, 16, v70
	global_store_dwordx4 v[2:3], v[128:131], off
	ds_read_u16 v80, v0 offset:4352
	ds_read_u16 v81, v0 offset:4624
	ds_read_u16 v82, v0 offset:4896
	ds_read_u16 v83, v0 offset:5168
	ds_read_u16 v84, v0 offset:5440
	ds_read_u16 v85, v0 offset:5712
	ds_read_u16 v86, v0 offset:5984
	ds_read_u16 v87, v0 offset:6256
	s_waitcnt lgkmcnt(8)
	v_lshl_or_b32 v138, v73, 16, v72
	v_lshl_or_b32 v139, v75, 16, v74
	v_lshl_or_b32 v140, v77, 16, v76
	v_lshl_or_b32 v141, v79, 16, v78
	global_store_dwordx4 v[2:3], v[138:141], off offset:16
	ds_read_u16 v64, v0 offset:6528
	ds_read_u16 v65, v0 offset:6800
	ds_read_u16 v66, v0 offset:7072
	ds_read_u16 v67, v0 offset:7344
	ds_read_u16 v68, v0 offset:7616
	ds_read_u16 v69, v0 offset:7888
	ds_read_u16 v70, v0 offset:8160
	ds_read_u16 v71, v0 offset:8432
	s_waitcnt lgkmcnt(8)
	v_lshl_or_b32 v128, v81, 16, v80
	v_lshl_or_b32 v129, v83, 16, v82
	v_lshl_or_b32 v130, v85, 16, v84
	v_lshl_or_b32 v131, v87, 16, v86
	global_store_dwordx4 v[2:3], v[128:131], off offset:32
	ds_read_u16 v72, v0 offset:8704
	ds_read_u16 v73, v0 offset:8976
	ds_read_u16 v74, v0 offset:9248
	ds_read_u16 v75, v0 offset:9520
	ds_read_u16 v76, v0 offset:9792
	ds_read_u16 v77, v0 offset:10064
	ds_read_u16 v78, v0 offset:10336
	ds_read_u16 v79, v0 offset:10608
	s_waitcnt lgkmcnt(8)
	v_lshl_or_b32 v138, v65, 16, v64
	v_lshl_or_b32 v139, v67, 16, v66
	v_lshl_or_b32 v140, v69, 16, v68
	v_lshl_or_b32 v141, v71, 16, v70
	global_store_dwordx4 v[2:3], v[138:141], off offset:48
	ds_read_u16 v80, v0 offset:10880
	ds_read_u16 v81, v0 offset:11152
	ds_read_u16 v82, v0 offset:11424
	ds_read_u16 v83, v0 offset:11696
	ds_read_u16 v84, v0 offset:11968
	ds_read_u16 v85, v0 offset:12240
	ds_read_u16 v86, v0 offset:12512
	ds_read_u16 v87, v0 offset:12784
	s_waitcnt lgkmcnt(8)
	v_lshl_or_b32 v128, v73, 16, v72
	v_lshl_or_b32 v129, v75, 16, v74
	v_lshl_or_b32 v130, v77, 16, v76
	v_lshl_or_b32 v131, v79, 16, v78
	global_store_dwordx4 v[2:3], v[128:131], off offset:64
	ds_read_u16 v64, v0 offset:13056
	ds_read_u16 v65, v0 offset:13328
	ds_read_u16 v66, v0 offset:13600
	ds_read_u16 v67, v0 offset:13872
	ds_read_u16 v68, v0 offset:14144
	ds_read_u16 v69, v0 offset:14416
	ds_read_u16 v70, v0 offset:14688
	ds_read_u16 v71, v0 offset:14960
	s_waitcnt lgkmcnt(8)
	v_lshl_or_b32 v138, v81, 16, v80
	v_lshl_or_b32 v139, v83, 16, v82
	v_lshl_or_b32 v140, v85, 16, v84
	v_lshl_or_b32 v141, v87, 16, v86
	global_store_dwordx4 v[2:3], v[138:141], off offset:80
	ds_read_u16 v72, v0 offset:15232
	ds_read_u16 v73, v0 offset:15504
	ds_read_u16 v74, v0 offset:15776
	ds_read_u16 v75, v0 offset:16048
	ds_read_u16 v76, v0 offset:16320
	ds_read_u16 v77, v0 offset:16592
	ds_read_u16 v78, v0 offset:16864
	ds_read_u16 v79, v0 offset:17136
	s_waitcnt lgkmcnt(8)
	v_lshl_or_b32 v128, v65, 16, v64
	v_lshl_or_b32 v129, v67, 16, v66
	v_lshl_or_b32 v130, v69, 16, v68
	v_lshl_or_b32 v131, v71, 16, v70
	global_store_dwordx4 v[2:3], v[128:131], off offset:96
	s_waitcnt lgkmcnt(0)
	v_lshl_or_b32 v138, v73, 16, v72
	v_lshl_or_b32 v139, v75, 16, v74
	v_lshl_or_b32 v140, v77, 16, v76
	v_lshl_or_b32 v141, v79, 16, v78
	global_store_dwordx4 v[2:3], v[138:141], off offset:112
	s_or_b64 exec, exec, s[16:17]
	s_and_saveexec_b64 s[16:17], s[12:13]
	s_cbranch_execz .LBB0_439
